# S5 carry scan loop rewritten by hand: 7 instr/step (fma form, packed bf16 cvt + d16_hi write), 16-chunk unrolled ping-pong prefetch
# baseline (speedup 1.0000x reference)
.Ls5s1_second:
	v_mfma_f32_16x16x32_bf16 v[72:75], v[132:135], v[0:3], 0
	v_mfma_f32_16x16x32_bf16 v[76:79], v[132:135], v[32:35], 0
	v_mfma_f32_16x16x32_bf16 v[72:75], v[136:139], v[4:7], v[72:75]
	v_mfma_f32_16x16x32_bf16 v[76:79], v[136:139], v[36:39], v[76:79]
	v_mfma_f32_16x16x32_bf16 v[72:75], v[140:143], v[8:11], v[72:75]
	v_mfma_f32_16x16x32_bf16 v[76:79], v[140:143], v[40:43], v[76:79]
	v_mfma_f32_16x16x32_bf16 v[72:75], v[144:147], v[12:15], v[72:75]
	v_mfma_f32_16x16x32_bf16 v[76:79], v[144:147], v[44:47], v[76:79]
	v_mfma_f32_16x16x32_bf16 v[72:75], v[148:151], v[16:19], v[72:75]
	v_mfma_f32_16x16x32_bf16 v[76:79], v[148:151], v[48:51], v[76:79]
	v_mfma_f32_16x16x32_bf16 v[72:75], v[152:155], v[20:23], v[72:75]
	v_mfma_f32_16x16x32_bf16 v[76:79], v[152:155], v[52:55], v[76:79]
	v_mfma_f32_16x16x32_bf16 v[72:75], v[156:159], v[24:27], v[72:75]
	v_mfma_f32_16x16x32_bf16 v[76:79], v[156:159], v[60:63], v[76:79]
	v_mfma_f32_16x16x32_bf16 v[72:75], v[160:163], v[28:31], v[72:75]
	v_mfma_f32_16x16x32_bf16 v[76:79], v[160:163], v[56:59], v[76:79]
	s_nop 7
	ds_write_b128 v66, v[72:75] offset:64
	ds_write_b128 v66, v[76:79] offset:8256
	v_add_u32_e32 v66, 0x80, v66
	s_cmp_lg_u32 s0, 0x10000
	s_cbranch_scc1 .LBB0_295
	s_or_b32 s92, s8, s3
	s_lshl_b64 s[0:1], s[92:93], 13
	s_add_u32 s0, s56, s0
	s_addc_u32 s1, s57, s1
	s_lshl_b64 s[8:9], s[92:93], 16
	v_add_u32_e32 v130, s33, v104
	s_add_u32 s8, s58, s8
	v_lshlrev_b32_e32 v96, 3, v130
	v_lshlrev_b32_e32 v64, 4, v104
	s_addc_u32 s9, s59, s9
	v_and_b32_e32 v100, 0xf0, v64
	v_mov_b32_e32 v101, v195
	v_and_b32_e32 v90, 0xffffff80, v96
	v_lshl_add_u64 v[88:89], s[8:9], 0, v[100:101]
	v_ashrrev_i32_e32 v91, 31, v90
	v_lshl_add_u64 v[64:65], v[90:91], 1, v[88:89]
	v_add_u32_e32 v66, 0x1000, v90
	v_add_u32_e32 v72, 0x2000, v90
	v_add_u32_e32 v74, 0x3000, v90
	v_add_u32_e32 v80, 0x4000, v90
	v_add_u32_e32 v82, 0x5000, v90
	v_add_u32_e32 v92, 0x6000, v90
	v_add_u32_e32 v90, 0x7000, v90
	v_ashrrev_i32_e32 v67, 31, v66
	v_ashrrev_i32_e32 v73, 31, v72
	v_ashrrev_i32_e32 v75, 31, v74
	v_ashrrev_i32_e32 v81, 31, v80
	v_ashrrev_i32_e32 v83, 31, v82
	v_ashrrev_i32_e32 v93, 31, v92
	v_ashrrev_i32_e32 v91, 31, v90
	v_ashrrev_i32_e32 v97, 31, v96
	v_lshl_add_u64 v[68:69], v[66:67], 1, v[88:89]
	v_lshl_add_u64 v[72:73], v[72:73], 1, v[88:89]
	v_lshl_add_u64 v[76:77], v[74:75], 1, v[88:89]
	v_lshl_add_u64 v[80:81], v[80:81], 1, v[88:89]
	v_lshl_add_u64 v[82:83], v[82:83], 1, v[88:89]
	v_lshl_add_u64 v[92:93], v[92:93], 1, v[88:89]
	v_lshl_add_u64 v[88:89], v[90:91], 1, v[88:89]
	v_lshl_add_u64 v[96:97], v[96:97], 1, s[0:1]
	s_waitcnt lgkmcnt(0)
	s_barrier
	global_load_dwordx4 v[64:67], v[64:65], off
	s_nop 0
	global_load_dwordx4 v[68:71], v[68:69], off
	s_nop 0
	global_load_dwordx4 v[72:75], v[72:73], off
	s_nop 0
	global_load_dwordx4 v[76:79], v[76:77], off
	s_nop 0
	global_load_dwordx4 v[84:87], v[80:81], off
	s_nop 0
	global_load_dwordx4 v[80:83], v[82:83], off
	s_nop 0
	global_load_dwordx4 v[92:95], v[92:93], off
	s_nop 0
	global_load_dwordx4 v[88:91], v[88:89], off
	s_andn2_b64 vcc, exec, s[40:41]
	global_load_dwordx4 v[96:99], v[96:97], off
	s_cbranch_vccnz .LBB0_299
	s_lshl_b32 s92, s92, 7
	s_lshl_b64 s[0:1], s[92:93], 2
	s_add_u32 s0, s34, s0
	v_lshlrev_b32_e32 v112, 1, v104
	s_addc_u32 s1, s35, s1
	v_ashrrev_i32_e32 v113, 31, v112
	v_lshl_add_u64 v[102:103], v[112:113], 2, s[0:1]
	global_load_dwordx2 v[102:103], v[102:103], off
	v_lshl_add_u32 v101, v104, 2, 0
	v_sub_u32_e32 v131, v101, v112
	ds_read2st64_b32 v[104:105], v101 offset0:0 offset1:1
	ds_read2st64_b32 v[106:107], v101 offset0:2 offset1:3
	ds_read2st64_b32 v[108:109], v101 offset0:4 offset1:5
	ds_read2st64_b32 v[110:111], v101 offset0:6 offset1:7
	ds_read2st64_b32 v[112:113], v101 offset0:8 offset1:9
	ds_read2st64_b32 v[114:115], v101 offset0:10 offset1:11
	ds_read2st64_b32 v[116:117], v101 offset0:12 offset1:13
	ds_read2st64_b32 v[118:119], v101 offset0:14 offset1:15
	v_mov_b32_e32 v122, 0
	v_mov_b32_e32 v123, 0
	s_mov_b32 s0, 0
	v_add_u32_e32 v149, 0x1000, v101
	s_waitcnt vmcnt(0) lgkmcnt(0)
.Ls5scan_loop:
	ds_read2st64_b32 v[132:133], v149 offset0:0 offset1:1
	ds_read2st64_b32 v[134:135], v149 offset0:2 offset1:3
	ds_read2st64_b32 v[136:137], v149 offset0:4 offset1:5
	ds_read2st64_b32 v[138:139], v149 offset0:6 offset1:7
	ds_read2st64_b32 v[140:141], v149 offset0:8 offset1:9
	ds_read2st64_b32 v[142:143], v149 offset0:10 offset1:11
	ds_read2st64_b32 v[144:145], v149 offset0:12 offset1:13
	ds_read2st64_b32 v[146:147], v149 offset0:14 offset1:15
	v_cvt_pk_bf16_f32 v148, v122, v123
	v_fma_f32 v120, -v103, v123, v104
	v_fma_f32 v121, v103, v122, v105
	ds_write_b16 v131, v148
	v_fma_f32 v120, v102, v122, v120
	v_fma_f32 v121, v102, v123, v121
	ds_write_b16_d16_hi v131, v148 offset:128
	v_cvt_pk_bf16_f32 v101, v120, v121
	v_fma_f32 v122, -v103, v121, v106
	v_fma_f32 v123, v103, v120, v107
	ds_write_b16 v131, v101 offset:512
	v_fma_f32 v122, v102, v120, v122
	v_fma_f32 v123, v102, v121, v123
	ds_write_b16_d16_hi v131, v101 offset:640
	v_cvt_pk_bf16_f32 v148, v122, v123
	v_fma_f32 v120, -v103, v123, v108
	v_fma_f32 v121, v103, v122, v109
	ds_write_b16 v131, v148 offset:1024
	v_fma_f32 v120, v102, v122, v120
	v_fma_f32 v121, v102, v123, v121
	ds_write_b16_d16_hi v131, v148 offset:1152
	v_cvt_pk_bf16_f32 v101, v120, v121
	v_fma_f32 v122, -v103, v121, v110
	v_fma_f32 v123, v103, v120, v111
	ds_write_b16 v131, v101 offset:1536
	v_fma_f32 v122, v102, v120, v122
	v_fma_f32 v123, v102, v121, v123
	ds_write_b16_d16_hi v131, v101 offset:1664
	v_cvt_pk_bf16_f32 v148, v122, v123
	v_fma_f32 v120, -v103, v123, v112
	v_fma_f32 v121, v103, v122, v113
	ds_write_b16 v131, v148 offset:2048
	v_fma_f32 v120, v102, v122, v120
	v_fma_f32 v121, v102, v123, v121
	ds_write_b16_d16_hi v131, v148 offset:2176
	v_cvt_pk_bf16_f32 v101, v120, v121
	v_fma_f32 v122, -v103, v121, v114
	v_fma_f32 v123, v103, v120, v115
	ds_write_b16 v131, v101 offset:2560
	v_fma_f32 v122, v102, v120, v122
	v_fma_f32 v123, v102, v121, v123
	ds_write_b16_d16_hi v131, v101 offset:2688
	v_cvt_pk_bf16_f32 v148, v122, v123
	v_fma_f32 v120, -v103, v123, v116
	v_fma_f32 v121, v103, v122, v117
	ds_write_b16 v131, v148 offset:3072
	v_fma_f32 v120, v102, v122, v120
	v_fma_f32 v121, v102, v123, v121
	ds_write_b16_d16_hi v131, v148 offset:3200
	v_cvt_pk_bf16_f32 v101, v120, v121
	v_fma_f32 v122, -v103, v121, v118
	v_fma_f32 v123, v103, v120, v119
	ds_write_b16 v131, v101 offset:3584
	v_fma_f32 v122, v102, v120, v122
	v_fma_f32 v123, v102, v121, v123
	ds_write_b16_d16_hi v131, v101 offset:3712
	v_add_u32_e32 v131, 0x1000, v131
	v_add_u32_e32 v149, 0x1000, v149
	s_waitcnt lgkmcnt(0)
	ds_read2st64_b32 v[104:105], v149 offset0:0 offset1:1
	ds_read2st64_b32 v[106:107], v149 offset0:2 offset1:3
	ds_read2st64_b32 v[108:109], v149 offset0:4 offset1:5
	ds_read2st64_b32 v[110:111], v149 offset0:6 offset1:7
	ds_read2st64_b32 v[112:113], v149 offset0:8 offset1:9
	ds_read2st64_b32 v[114:115], v149 offset0:10 offset1:11
	ds_read2st64_b32 v[116:117], v149 offset0:12 offset1:13
	ds_read2st64_b32 v[118:119], v149 offset0:14 offset1:15
	v_cvt_pk_bf16_f32 v148, v122, v123
	v_fma_f32 v120, -v103, v123, v132
	v_fma_f32 v121, v103, v122, v133
	ds_write_b16 v131, v148
	v_fma_f32 v120, v102, v122, v120
	v_fma_f32 v121, v102, v123, v121
	ds_write_b16_d16_hi v131, v148 offset:128
	v_cvt_pk_bf16_f32 v101, v120, v121
	v_fma_f32 v122, -v103, v121, v134
	v_fma_f32 v123, v103, v120, v135
	ds_write_b16 v131, v101 offset:512
	v_fma_f32 v122, v102, v120, v122
	v_fma_f32 v123, v102, v121, v123
	ds_write_b16_d16_hi v131, v101 offset:640
	v_cvt_pk_bf16_f32 v148, v122, v123
	v_fma_f32 v120, -v103, v123, v136
	v_fma_f32 v121, v103, v122, v137
	ds_write_b16 v131, v148 offset:1024
	v_fma_f32 v120, v102, v122, v120
	v_fma_f32 v121, v102, v123, v121
	ds_write_b16_d16_hi v131, v148 offset:1152
	v_cvt_pk_bf16_f32 v101, v120, v121
	v_fma_f32 v122, -v103, v121, v138
	v_fma_f32 v123, v103, v120, v139
	ds_write_b16 v131, v101 offset:1536
	v_fma_f32 v122, v102, v120, v122
	v_fma_f32 v123, v102, v121, v123
	ds_write_b16_d16_hi v131, v101 offset:1664
	v_cvt_pk_bf16_f32 v148, v122, v123
	v_fma_f32 v120, -v103, v123, v140
	v_fma_f32 v121, v103, v122, v141
	ds_write_b16 v131, v148 offset:2048
	v_fma_f32 v120, v102, v122, v120
	v_fma_f32 v121, v102, v123, v121
	ds_write_b16_d16_hi v131, v148 offset:2176
	v_cvt_pk_bf16_f32 v101, v120, v121
	v_fma_f32 v122, -v103, v121, v142
	v_fma_f32 v123, v103, v120, v143
	ds_write_b16 v131, v101 offset:2560
	v_fma_f32 v122, v102, v120, v122
	v_fma_f32 v123, v102, v121, v123
	ds_write_b16_d16_hi v131, v101 offset:2688
	v_cvt_pk_bf16_f32 v148, v122, v123
	v_fma_f32 v120, -v103, v123, v144
	v_fma_f32 v121, v103, v122, v145
	ds_write_b16 v131, v148 offset:3072
	v_fma_f32 v120, v102, v122, v120
	v_fma_f32 v121, v102, v123, v121
	ds_write_b16_d16_hi v131, v148 offset:3200
	v_cvt_pk_bf16_f32 v101, v120, v121
	v_fma_f32 v122, -v103, v121, v146
	v_fma_f32 v123, v103, v120, v147
	ds_write_b16 v131, v101 offset:3584
	v_fma_f32 v122, v102, v120, v122
	v_fma_f32 v123, v102, v121, v123
	ds_write_b16_d16_hi v131, v101 offset:3712
	v_add_u32_e32 v131, 0x1000, v131
	v_add_u32_e32 v149, 0x1000, v149
	s_add_i32 s0, s0, 1
	s_cmp_lt_u32 s0, 16
	s_waitcnt lgkmcnt(0)
	s_cbranch_scc1 .Ls5scan_loop
